# O-proj residual epilogue: accumulators moved across lanes (ds_bpermute) so 4 adjacent lanes cover one 64-byte row segment for the x loads/stores
# baseline (speedup 1.0000x reference)
.LBB0_346:
	v_and_b32_e32 v20, 15, v1
	v_bfe_u32 v19, v1, 4, 2
	v_bfe_u32 v241, v1, 2, 4
	v_and_b32_e32 v242, 3, v1
	v_lshlrev_b32_e32 v240, 6, v242
	v_lshl_or_b32 v240, v241, 2, v240
	v_lshlrev_b32_e32 v21, 6, v20
	v_lshlrev_b32_e32 v1, 2, v1
	s_sext_i32_i8 s85, s4
	v_lshl_or_b32 v21, v19, 4, v21
	s_lshl_b32 s4, s5, 13
	v_and_b32_e32 v1, 32, v1
	v_bitop3_b32 v22, v21, s4, v1 bitop3:0xde
	s_lshl_b32 s4, s6, 5
	s_and_b32 s4, s4, 0x60
	s_lshl_b32 s6, s4, 7
	s_add_u32 s79, s88, 0xd822000
	s_addc_u32 s80, s89, 0
	s_add_i32 m0, s19, 0x18000
	v_lshl_add_u64 v[10:11], v[10:11], 0, s[24:25]
	s_waitcnt vmcnt(4)
	s_barrier
	global_load_lds_dwordx4 v[10:11], off
	v_lshl_add_u64 v[8:9], v[8:9], 0, s[24:25]
	s_add_i32 m0, s19, 0x1a000
	s_add_i32 s81, s19, 0x8000
	s_add_i32 s82, s19, 0xa000
	v_bitop3_b32 v1, v21, s6, v1 bitop3:0xde
	global_load_lds_dwordx4 v[8:9], off
	v_lshl_add_u64 v[6:7], v[6:7], 0, s[24:25]
	s_mov_b32 m0, s81
	s_add_u32 s6, s46, 0x40080
	global_load_lds_dwordx4 v[6:7], off
	v_lshl_add_u64 v[4:5], v[4:5], 0, s[24:25]
	s_mov_b32 m0, s82
	s_addc_u32 s7, s47, 0
	global_load_lds_dwordx4 v[4:5], off
	s_add_i32 m0, s19, 0x1c000
	v_lshl_add_u64 v[4:5], s[6:7], 0, v[150:151]
	global_load_lds_dwordx4 v[4:5], off
	v_lshl_add_u64 v[4:5], s[6:7], 0, v[152:153]
	s_add_i32 m0, s19, 0x1e000
	v_lshlrev_b32_e32 v2, 13, v2
	global_load_lds_dwordx4 v[4:5], off
	v_and_b32_e32 v2, 0x7fffc000, v2
	v_lshl_add_u32 v2, v12, 10, v2
	v_lshlrev_b32_e32 v4, 10, v241
	v_or_b32_e32 v2, v2, v13
	v_lshl_or_b32 v37, s5, 16, v4
	v_lshl_or_b32 v154, v242, 2, s4
	v_add_lshl_u32 v2, v2, v14, 1
	s_mov_b64 s[4:5], 0x40080
	v_lshl_add_u64 v[162:163], v[2:3], 0, s[4:5]
	v_lshlrev_b32_e32 v2, 13, v15
	v_and_b32_e32 v2, 0x7fffc000, v2
	v_lshl_add_u32 v2, v16, 10, v2
	s_waitcnt vmcnt(6)
	v_or_b32_e32 v2, v2, v17
	v_add_lshl_u32 v2, v2, v18, 1
	s_ashr_i32 s83, s96, 31
	v_lshl_add_u64 v[164:165], v[2:3], 0, s[4:5]
	s_mov_b32 s84, 0
	v_add_u32_e32 v155, 0, v22
	s_barrier
	s_branch .LBB0_348
.LBB0_347:
	s_cmp_lt_i32 s18, 24
	s_cselect_b32 s7, s67, 0x3000
	s_cmp_gt_i32 s18, 15
	s_cselect_b32 s7, s7, 0
	v_lshl_or_b32 v134, s85, 8, v154
	s_lshl_b32 s7, s7, 2
	v_add_u32_e32 v2, v37, v134
	s_add_u32 s46, s79, s7
	s_addc_u32 s47, s80, 0
	v_ashrrev_i32_e32 v135, 31, v134
	v_lshl_add_u64 v[136:137], v[134:135], 2, s[46:47]
	global_load_dwordx4 v[146:149], v[136:137], off
	s_add_u32 s44, s0, s44
	s_addc_u32 s45, s1, s45
	global_load_dwordx4 v[142:145], v[136:137], off offset:64
	global_load_dwordx4 v[138:141], v[136:137], off offset:512
	s_nop 0
	global_load_dwordx4 v[134:137], v[136:137], off offset:576
	s_mov_b32 s85, s6
	s_mov_b64 s[46:47], s[16:17]
	s_mov_b32 s18, s12
	s_and_b64 vcc, exec, s[4:5]
	v_mov_b32_e32 v210, v2
	v_mov_b32_e32 v211, v3
	v_lshlrev_b64 v[210:211], 2, v[210:211]
	v_lshl_add_u64 v[212:213], s[38:39], 0, v[210:211]
	global_load_dwordx4 v[156:159], v[212:213], off
	global_load_dwordx4 v[166:169], v[212:213], off offset:64
	global_load_dwordx4 v[170:173], v[212:213], off offset:512
	global_load_dwordx4 v[174:177], v[212:213], off offset:576
	v_add_u32_e32 v210, 0x4000, v2
	v_mov_b32_e32 v211, v3
	v_lshlrev_b64 v[210:211], 2, v[210:211]
	v_lshl_add_u64 v[212:213], s[38:39], 0, v[210:211]
	global_load_dwordx4 v[178:181], v[212:213], off
	global_load_dwordx4 v[182:185], v[212:213], off offset:64
	global_load_dwordx4 v[186:189], v[212:213], off offset:512
	global_load_dwordx4 v[190:193], v[212:213], off offset:576
	v_add_u32_e32 v210, 0x8000, v2
	v_mov_b32_e32 v211, v3
	v_lshlrev_b64 v[210:211], 2, v[210:211]
	v_lshl_add_u64 v[212:213], s[38:39], 0, v[210:211]
	global_load_dwordx4 v[194:197], v[212:213], off
	global_load_dwordx4 v[198:201], v[212:213], off offset:64
	global_load_dwordx4 v[202:205], v[212:213], off offset:512
	global_load_dwordx4 v[206:209], v[212:213], off offset:576
	v_mov_b32_e32 v210, v2
	v_mov_b32_e32 v211, v3
	v_lshlrev_b64 v[210:211], 2, v[210:211]
	v_lshl_add_u64 v[214:215], s[44:45], 0, v[210:211]
	ds_bpermute_b32 v4, v240, v4
	ds_bpermute_b32 v5, v240, v5
	ds_bpermute_b32 v6, v240, v6
	ds_bpermute_b32 v7, v240, v7
	ds_bpermute_b32 v8, v240, v8
	ds_bpermute_b32 v9, v240, v9
	ds_bpermute_b32 v10, v240, v10
	ds_bpermute_b32 v11, v240, v11
	ds_bpermute_b32 v12, v240, v12
	ds_bpermute_b32 v13, v240, v13
	ds_bpermute_b32 v14, v240, v14
	ds_bpermute_b32 v15, v240, v15
	s_waitcnt lgkmcnt(0)
	ds_bpermute_b32 v16, v240, v16
	ds_bpermute_b32 v17, v240, v17
	ds_bpermute_b32 v18, v240, v18
	ds_bpermute_b32 v19, v240, v19
	ds_bpermute_b32 v20, v240, v20
	ds_bpermute_b32 v21, v240, v21
	ds_bpermute_b32 v22, v240, v22
	ds_bpermute_b32 v23, v240, v23
	ds_bpermute_b32 v24, v240, v24
	ds_bpermute_b32 v25, v240, v25
	ds_bpermute_b32 v26, v240, v26
	ds_bpermute_b32 v27, v240, v27
	s_waitcnt lgkmcnt(0)
	ds_bpermute_b32 v28, v240, v28
	ds_bpermute_b32 v29, v240, v29
	ds_bpermute_b32 v30, v240, v30
	ds_bpermute_b32 v31, v240, v31
	ds_bpermute_b32 v32, v240, v32
	ds_bpermute_b32 v33, v240, v33
	ds_bpermute_b32 v34, v240, v34
	ds_bpermute_b32 v35, v240, v35
	ds_bpermute_b32 v38, v240, v38
	ds_bpermute_b32 v39, v240, v39
	ds_bpermute_b32 v40, v240, v40
	ds_bpermute_b32 v41, v240, v41
	s_waitcnt lgkmcnt(0)
	ds_bpermute_b32 v42, v240, v42
	ds_bpermute_b32 v43, v240, v43
	ds_bpermute_b32 v44, v240, v44
	ds_bpermute_b32 v45, v240, v45
	ds_bpermute_b32 v46, v240, v46
	ds_bpermute_b32 v47, v240, v47
	ds_bpermute_b32 v48, v240, v48
	ds_bpermute_b32 v49, v240, v49
	ds_bpermute_b32 v50, v240, v50
	ds_bpermute_b32 v51, v240, v51
	ds_bpermute_b32 v52, v240, v52
	ds_bpermute_b32 v53, v240, v53
	s_waitcnt lgkmcnt(0)
	ds_bpermute_b32 v54, v240, v54
	ds_bpermute_b32 v55, v240, v55
	ds_bpermute_b32 v56, v240, v56
	ds_bpermute_b32 v57, v240, v57
	ds_bpermute_b32 v58, v240, v58
	ds_bpermute_b32 v59, v240, v59
	ds_bpermute_b32 v60, v240, v60
	ds_bpermute_b32 v61, v240, v61
	ds_bpermute_b32 v62, v240, v62
	ds_bpermute_b32 v63, v240, v63
	ds_bpermute_b32 v64, v240, v64
	ds_bpermute_b32 v65, v240, v65
	s_waitcnt lgkmcnt(0)
	ds_bpermute_b32 v66, v240, v66
	ds_bpermute_b32 v67, v240, v67
	ds_bpermute_b32 v68, v240, v68
	ds_bpermute_b32 v69, v240, v69
	ds_bpermute_b32 v70, v240, v70
	ds_bpermute_b32 v71, v240, v71
	ds_bpermute_b32 v72, v240, v72
	ds_bpermute_b32 v73, v240, v73
	ds_bpermute_b32 v74, v240, v74
	ds_bpermute_b32 v75, v240, v75
	ds_bpermute_b32 v76, v240, v76
	ds_bpermute_b32 v77, v240, v77
	s_waitcnt lgkmcnt(0)
	ds_bpermute_b32 v78, v240, v78
	ds_bpermute_b32 v79, v240, v79
	ds_bpermute_b32 v80, v240, v80
	ds_bpermute_b32 v81, v240, v81
	ds_bpermute_b32 v82, v240, v82
	ds_bpermute_b32 v83, v240, v83
	ds_bpermute_b32 v84, v240, v84
	ds_bpermute_b32 v85, v240, v85
	ds_bpermute_b32 v86, v240, v86
	ds_bpermute_b32 v87, v240, v87
	ds_bpermute_b32 v88, v240, v88
	ds_bpermute_b32 v89, v240, v89
	s_waitcnt lgkmcnt(0)
	ds_bpermute_b32 v90, v240, v90
	ds_bpermute_b32 v91, v240, v91
	ds_bpermute_b32 v92, v240, v92
	ds_bpermute_b32 v93, v240, v93
	ds_bpermute_b32 v94, v240, v94
	ds_bpermute_b32 v95, v240, v95
	ds_bpermute_b32 v96, v240, v96
	ds_bpermute_b32 v97, v240, v97
	ds_bpermute_b32 v98, v240, v98
	ds_bpermute_b32 v99, v240, v99
	ds_bpermute_b32 v100, v240, v100
	ds_bpermute_b32 v101, v240, v101
	s_waitcnt lgkmcnt(0)
	ds_bpermute_b32 v102, v240, v102
	ds_bpermute_b32 v103, v240, v103
	ds_bpermute_b32 v104, v240, v104
	ds_bpermute_b32 v105, v240, v105
	ds_bpermute_b32 v106, v240, v106
	ds_bpermute_b32 v107, v240, v107
	ds_bpermute_b32 v108, v240, v108
	ds_bpermute_b32 v109, v240, v109
	ds_bpermute_b32 v110, v240, v110
	ds_bpermute_b32 v111, v240, v111
	ds_bpermute_b32 v112, v240, v112
	ds_bpermute_b32 v113, v240, v113
	s_waitcnt lgkmcnt(0)
	ds_bpermute_b32 v114, v240, v114
	ds_bpermute_b32 v115, v240, v115
	ds_bpermute_b32 v116, v240, v116
	ds_bpermute_b32 v117, v240, v117
	ds_bpermute_b32 v118, v240, v118
	ds_bpermute_b32 v119, v240, v119
	ds_bpermute_b32 v120, v240, v120
	ds_bpermute_b32 v121, v240, v121
	ds_bpermute_b32 v122, v240, v122
	ds_bpermute_b32 v123, v240, v123
	ds_bpermute_b32 v124, v240, v124
	ds_bpermute_b32 v125, v240, v125
	s_waitcnt lgkmcnt(0)
	ds_bpermute_b32 v126, v240, v126
	ds_bpermute_b32 v127, v240, v127
	ds_bpermute_b32 v128, v240, v128
	ds_bpermute_b32 v129, v240, v129
	ds_bpermute_b32 v130, v240, v130
	ds_bpermute_b32 v131, v240, v131
	ds_bpermute_b32 v132, v240, v132
	ds_bpermute_b32 v133, v240, v133
	s_waitcnt lgkmcnt(0)
	s_waitcnt vmcnt(11)
	v_pk_fma_f32 v[132:133], v[132:133], v[148:149], v[158:159]
	v_pk_fma_f32 v[130:131], v[130:131], v[146:147], v[156:157]
	global_store_dwordx4 v[214:215], v[130:133], off
	v_add_u32_e32 v210, 0xc000, v2
	v_mov_b32_e32 v211, v3
	v_lshlrev_b64 v[210:211], 2, v[210:211]
	v_lshl_add_u64 v[212:213], s[38:39], 0, v[210:211]
	global_load_dwordx4 v[156:159], v[212:213], off
	s_waitcnt vmcnt(12)
	v_pk_fma_f32 v[128:129], v[128:129], v[144:145], v[168:169]
	v_pk_fma_f32 v[126:127], v[126:127], v[142:143], v[166:167]
	global_store_dwordx4 v[214:215], v[126:129], off offset:64
	global_load_dwordx4 v[166:169], v[212:213], off offset:64
	s_waitcnt vmcnt(13)
	v_pk_fma_f32 v[124:125], v[124:125], v[140:141], v[172:173]
	v_pk_fma_f32 v[122:123], v[122:123], v[138:139], v[170:171]
	global_store_dwordx4 v[214:215], v[122:125], off offset:512
	global_load_dwordx4 v[170:173], v[212:213], off offset:512
	s_waitcnt vmcnt(14)
	v_pk_fma_f32 v[116:117], v[116:117], v[136:137], v[176:177]
	v_pk_fma_f32 v[114:115], v[114:115], v[134:135], v[174:175]
	global_store_dwordx4 v[214:215], v[114:117], off offset:576
	global_load_dwordx4 v[174:177], v[212:213], off offset:576
	v_add_u32_e32 v210, 0x4000, v2
	v_mov_b32_e32 v211, v3
	v_lshlrev_b64 v[210:211], 2, v[210:211]
	v_lshl_add_u64 v[214:215], s[44:45], 0, v[210:211]
	s_waitcnt vmcnt(15)
	v_pk_fma_f32 v[120:121], v[120:121], v[148:149], v[180:181]
	v_pk_fma_f32 v[118:119], v[118:119], v[146:147], v[178:179]
	global_store_dwordx4 v[214:215], v[118:121], off
	v_add_u32_e32 v210, 0x20000, v2
	v_mov_b32_e32 v211, v3
	v_lshlrev_b64 v[210:211], 2, v[210:211]
	v_lshl_add_u64 v[212:213], s[38:39], 0, v[210:211]
	global_load_dwordx4 v[178:181], v[212:213], off
	s_waitcnt vmcnt(16)
	v_pk_fma_f32 v[112:113], v[112:113], v[144:145], v[184:185]
	v_pk_fma_f32 v[110:111], v[110:111], v[142:143], v[182:183]
	global_store_dwordx4 v[214:215], v[110:113], off offset:64
	global_load_dwordx4 v[182:185], v[212:213], off offset:64
	s_waitcnt vmcnt(17)
	v_pk_fma_f32 v[108:109], v[108:109], v[140:141], v[188:189]
	v_pk_fma_f32 v[106:107], v[106:107], v[138:139], v[186:187]
	global_store_dwordx4 v[214:215], v[106:109], off offset:512
	global_load_dwordx4 v[186:189], v[212:213], off offset:512
	s_waitcnt vmcnt(18)
	v_pk_fma_f32 v[100:101], v[100:101], v[136:137], v[192:193]
	v_pk_fma_f32 v[98:99], v[98:99], v[134:135], v[190:191]
	global_store_dwordx4 v[214:215], v[98:101], off offset:576
	global_load_dwordx4 v[190:193], v[212:213], off offset:576
	v_add_u32_e32 v210, 0x8000, v2
	v_mov_b32_e32 v211, v3
	v_lshlrev_b64 v[210:211], 2, v[210:211]
	v_lshl_add_u64 v[214:215], s[44:45], 0, v[210:211]
	s_waitcnt vmcnt(19)
	v_pk_fma_f32 v[104:105], v[104:105], v[148:149], v[196:197]
	v_pk_fma_f32 v[102:103], v[102:103], v[146:147], v[194:195]
	global_store_dwordx4 v[214:215], v[102:105], off
	v_add_u32_e32 v210, 0x24000, v2
	v_mov_b32_e32 v211, v3
	v_lshlrev_b64 v[210:211], 2, v[210:211]
	v_lshl_add_u64 v[212:213], s[38:39], 0, v[210:211]
	global_load_dwordx4 v[194:197], v[212:213], off
	s_waitcnt vmcnt(20)
	v_pk_fma_f32 v[96:97], v[96:97], v[144:145], v[200:201]
	v_pk_fma_f32 v[94:95], v[94:95], v[142:143], v[198:199]
	global_store_dwordx4 v[214:215], v[94:97], off offset:64
	global_load_dwordx4 v[198:201], v[212:213], off offset:64
	s_waitcnt vmcnt(21)
	v_pk_fma_f32 v[92:93], v[92:93], v[140:141], v[204:205]
	v_pk_fma_f32 v[90:91], v[90:91], v[138:139], v[202:203]
	global_store_dwordx4 v[214:215], v[90:93], off offset:512
	global_load_dwordx4 v[202:205], v[212:213], off offset:512
	s_waitcnt vmcnt(22)
	v_pk_fma_f32 v[84:85], v[84:85], v[136:137], v[208:209]
	v_pk_fma_f32 v[82:83], v[82:83], v[134:135], v[206:207]
	global_store_dwordx4 v[214:215], v[82:85], off offset:576
	global_load_dwordx4 v[206:209], v[212:213], off offset:576
	v_add_u32_e32 v210, 0xc000, v2
	v_mov_b32_e32 v211, v3
	v_lshlrev_b64 v[210:211], 2, v[210:211]
	v_lshl_add_u64 v[214:215], s[44:45], 0, v[210:211]
	s_waitcnt vmcnt(22)
	v_pk_fma_f32 v[88:89], v[88:89], v[148:149], v[158:159]
	v_pk_fma_f32 v[86:87], v[86:87], v[146:147], v[156:157]
	global_store_dwordx4 v[214:215], v[86:89], off
	v_add_u32_e32 v210, 0x28000, v2
	v_mov_b32_e32 v211, v3
	v_lshlrev_b64 v[210:211], 2, v[210:211]
	v_lshl_add_u64 v[212:213], s[38:39], 0, v[210:211]
	global_load_dwordx4 v[156:159], v[212:213], off
	s_waitcnt vmcnt(22)
	v_pk_fma_f32 v[80:81], v[80:81], v[144:145], v[168:169]
	v_pk_fma_f32 v[78:79], v[78:79], v[142:143], v[166:167]
	global_store_dwordx4 v[214:215], v[78:81], off offset:64
	global_load_dwordx4 v[166:169], v[212:213], off offset:64
	s_waitcnt vmcnt(22)
	v_pk_fma_f32 v[76:77], v[76:77], v[140:141], v[172:173]
	v_pk_fma_f32 v[74:75], v[74:75], v[138:139], v[170:171]
	global_store_dwordx4 v[214:215], v[74:77], off offset:512
	global_load_dwordx4 v[170:173], v[212:213], off offset:512
	s_waitcnt vmcnt(22)
	v_pk_fma_f32 v[72:73], v[72:73], v[136:137], v[176:177]
	v_pk_fma_f32 v[70:71], v[70:71], v[134:135], v[174:175]
	global_store_dwordx4 v[214:215], v[70:73], off offset:576
	global_load_dwordx4 v[174:177], v[212:213], off offset:576
	v_add_u32_e32 v210, 0x20000, v2
	v_mov_b32_e32 v211, v3
	v_lshlrev_b64 v[210:211], 2, v[210:211]
	v_lshl_add_u64 v[214:215], s[44:45], 0, v[210:211]
	s_waitcnt vmcnt(22)
	v_pk_fma_f32 v[68:69], v[68:69], v[148:149], v[180:181]
	v_pk_fma_f32 v[66:67], v[66:67], v[146:147], v[178:179]
	global_store_dwordx4 v[214:215], v[66:69], off
	v_add_u32_e32 v210, 0x2c000, v2
	v_mov_b32_e32 v211, v3
	v_lshlrev_b64 v[210:211], 2, v[210:211]
	v_lshl_add_u64 v[212:213], s[38:39], 0, v[210:211]
	global_load_dwordx4 v[178:181], v[212:213], off
	s_waitcnt vmcnt(22)
	v_pk_fma_f32 v[64:65], v[64:65], v[144:145], v[184:185]
	v_pk_fma_f32 v[62:63], v[62:63], v[142:143], v[182:183]
	global_store_dwordx4 v[214:215], v[62:65], off offset:64
	global_load_dwordx4 v[182:185], v[212:213], off offset:64
	s_waitcnt vmcnt(22)
	v_pk_fma_f32 v[60:61], v[60:61], v[140:141], v[188:189]
	v_pk_fma_f32 v[58:59], v[58:59], v[138:139], v[186:187]
	global_store_dwordx4 v[214:215], v[58:61], off offset:512
	global_load_dwordx4 v[186:189], v[212:213], off offset:512
	s_waitcnt vmcnt(22)
	v_pk_fma_f32 v[52:53], v[52:53], v[136:137], v[192:193]
	v_pk_fma_f32 v[50:51], v[50:51], v[134:135], v[190:191]
	global_store_dwordx4 v[214:215], v[50:53], off offset:576
	global_load_dwordx4 v[190:193], v[212:213], off offset:576
	v_add_u32_e32 v210, 0x24000, v2
	v_mov_b32_e32 v211, v3
	v_lshlrev_b64 v[210:211], 2, v[210:211]
	v_lshl_add_u64 v[214:215], s[44:45], 0, v[210:211]
	s_waitcnt vmcnt(22)
	v_pk_fma_f32 v[56:57], v[56:57], v[148:149], v[196:197]
	v_pk_fma_f32 v[54:55], v[54:55], v[146:147], v[194:195]
	global_store_dwordx4 v[214:215], v[54:57], off
	s_waitcnt vmcnt(21)
	v_pk_fma_f32 v[48:49], v[48:49], v[144:145], v[200:201]
	v_pk_fma_f32 v[46:47], v[46:47], v[142:143], v[198:199]
	global_store_dwordx4 v[214:215], v[46:49], off offset:64
	s_waitcnt vmcnt(20)
	v_pk_fma_f32 v[44:45], v[44:45], v[140:141], v[204:205]
	v_pk_fma_f32 v[42:43], v[42:43], v[138:139], v[202:203]
	global_store_dwordx4 v[214:215], v[42:45], off offset:512
	s_waitcnt vmcnt(19)
	v_pk_fma_f32 v[34:35], v[34:35], v[136:137], v[208:209]
	v_pk_fma_f32 v[32:33], v[32:33], v[134:135], v[206:207]
	global_store_dwordx4 v[214:215], v[32:35], off offset:576
	v_add_u32_e32 v210, 0x28000, v2
	v_mov_b32_e32 v211, v3
	v_lshlrev_b64 v[210:211], 2, v[210:211]
	v_lshl_add_u64 v[214:215], s[44:45], 0, v[210:211]
	s_waitcnt vmcnt(18)
	v_pk_fma_f32 v[40:41], v[40:41], v[148:149], v[158:159]
	v_pk_fma_f32 v[38:39], v[38:39], v[146:147], v[156:157]
	global_store_dwordx4 v[214:215], v[38:41], off
	s_waitcnt vmcnt(17)
	v_pk_fma_f32 v[30:31], v[30:31], v[144:145], v[168:169]
	v_pk_fma_f32 v[28:29], v[28:29], v[142:143], v[166:167]
	global_store_dwordx4 v[214:215], v[28:31], off offset:64
	s_waitcnt vmcnt(16)
	v_pk_fma_f32 v[26:27], v[26:27], v[140:141], v[172:173]
	v_pk_fma_f32 v[24:25], v[24:25], v[138:139], v[170:171]
	global_store_dwordx4 v[214:215], v[24:27], off offset:512
	s_waitcnt vmcnt(15)
	v_pk_fma_f32 v[18:19], v[18:19], v[136:137], v[176:177]
	v_pk_fma_f32 v[16:17], v[16:17], v[134:135], v[174:175]
	global_store_dwordx4 v[214:215], v[16:19], off offset:576
	v_add_u32_e32 v210, 0x2c000, v2
	v_mov_b32_e32 v211, v3
	v_lshlrev_b64 v[210:211], 2, v[210:211]
	v_lshl_add_u64 v[214:215], s[44:45], 0, v[210:211]
	s_waitcnt vmcnt(14)
	v_pk_fma_f32 v[22:23], v[22:23], v[148:149], v[180:181]
	v_pk_fma_f32 v[20:21], v[20:21], v[146:147], v[178:179]
	global_store_dwordx4 v[214:215], v[20:23], off
	s_waitcnt vmcnt(13)
	v_pk_fma_f32 v[14:15], v[14:15], v[144:145], v[184:185]
	v_pk_fma_f32 v[12:13], v[12:13], v[142:143], v[182:183]
	global_store_dwordx4 v[214:215], v[12:15], off offset:64
	s_waitcnt vmcnt(12)
	v_pk_fma_f32 v[10:11], v[10:11], v[140:141], v[188:189]
	v_pk_fma_f32 v[8:9], v[8:9], v[138:139], v[186:187]
	global_store_dwordx4 v[214:215], v[8:11], off offset:512
	s_waitcnt vmcnt(11)
	v_pk_fma_f32 v[6:7], v[6:7], v[136:137], v[192:193]
	v_pk_fma_f32 v[4:5], v[4:5], v[134:135], v[190:191]
	global_store_dwordx4 v[214:215], v[4:7], off offset:576
	s_mov_b64 s[38:39], s[14:15]
	s_cbranch_vccnz .LBB0_363
